# attention queue order: the dilation-16 (half-length) units are handed out last so the end-of-phase tail is a short unit
# baseline (speedup 1.0000x reference)
; DI void attn_unit(LAS unsigned char* lds, const bf16* P, bf16* OG, float* LSE, const float* relb, int u) {
;     ...
;     const int bp = u & 7, t2 = u >> 3, head = t2 % 12, bl = t2 / 12, g = head >> 2, hs = head & 3;
; __global__ void __launch_bounds__(512, 2) fwd_mega(Args a) {
;     ...
;                 int u = s_unit[0], par = 0;
;                 while (u < 1536) {
;                     int nxt = 0;
;                     if (tid == 0) nxt = (int)atomicAdd(ctr, 1u);
;                     attn_unit(lds, P, OG, LSE, a.in[12], u);
.LBB0_407:
	s_and_b32 s5, s18, 7
	s_lshr_b32 s4, s18, 3
	s_cmpk_lt_u32 s18, 0x400
	s_cbranch_scc0 .Luo_light
	s_lshr_b32 s6, s4, 3
	s_and_b32 s4, s4, 7
	s_branch .Luo_join
.Luo_light:
	s_addk_i32 s4, 0xff80
	s_lshr_b32 s6, s4, 2
	s_and_b32 s4, s4, 3
	s_add_i32 s4, s4, 8
.Luo_join:
	s_mul_i32 s6, s6, 12
	s_add_i32 s4, s4, s6
	s_lshl_b32 s4, s4, 3
	s_or_b32 s18, s4, s5
	v_mov_b32_e32 v182, 0
	s_and_saveexec_b64 s[4:5], s[0:1]
	s_cbranch_execz .LBB0_411
	s_mov_b64 s[8:9], exec
	v_mbcnt_lo_u32_b32 v0, s8, 0
	v_mbcnt_hi_u32_b32 v0, s9, v0
	v_cmp_eq_u32_e32 vcc, 0, v0
	s_and_saveexec_b64 s[6:7], vcc
	s_cbranch_execz .LBB0_410
	s_bcnt1_i32_b64 s8, s[8:9]
	v_mov_b32_e32 v2, s8
	global_atomic_add v219, v1, v2, s[2:3] sc0
